# attention k-loop: Q-fragment LDS reads batched ahead of the QK MFMAs
# speedup vs baseline: 1.0078x; 1.0078x over previous
; __device__ __forceinline__ void mixer_unit(LAS unsigned char* lds, int unit, const bf16* P, bf16* Y, const float* conv_w, const float* sgu_norm, const float* sgu_w, const float* sgu_b, int tid, int wave, int lane) {
;     ...
;         for (int k0 = t0 + 32;; k0 -= 32) {
;             const bool doA = actA && (k0 <= t0);
;             f32x16 zB = {}, zA = {};
;             if (actB) {
; #pragma unroll
;                 for (int ks = 0; ks < 4; ++ks) zB = __builtin_amdgcn_mfma_f32_32x32x16_bf16(kfn[ks], Qs[(4 + ks) * 64 + lane], zB, 0, 0, 0); }
;             if (doA) {
; #pragma unroll
;                 for (int ks = 0; ks < 4; ++ks) zA = __builtin_amdgcn_mfma_f32_32x32x16_bf16(kfn[ks], Qs[ks * 64 + lane], zA, 0, 0, 0); }
.LBB0_172:
	s_waitcnt vmcnt(4)
	v_mov_b64_e32 v[162:163], v[142:143]
	v_mov_b64_e32 v[166:167], v[138:139]
	v_mov_b64_e32 v[170:171], v[134:135]
	v_mov_b64_e32 v[174:175], v[130:131]
	s_waitcnt vmcnt(0)
	v_mov_b64_e32 v[178:179], v[158:159]
	v_mov_b64_e32 v[182:183], v[154:155]
	v_mov_b64_e32 v[186:187], v[150:151]
	v_mov_b64_e32 v[190:191], v[146:147]
	v_cndmask_b32_e64 v65, 0, 1, s[6:7]
	v_mov_b64_e32 v[160:161], v[140:141]
	v_mov_b64_e32 v[164:165], v[136:137]
	v_mov_b64_e32 v[168:169], v[132:133]
	v_mov_b64_e32 v[172:173], v[128:129]
	v_mov_b64_e32 v[176:177], v[156:157]
	v_mov_b64_e32 v[180:181], v[152:153]
	v_mov_b64_e32 v[184:185], v[148:149]
	v_mov_b64_e32 v[188:189], v[144:145]
	v_mov_b32_e32 v64, 0
	v_cmp_ne_u32_e64 s[42:43], 1, v65
	s_andn2_b64 vcc, exec, s[6:7]
	v_mov_b32_e32 v80, 0
	v_mov_b32_e32 v81, 0
	v_mov_b32_e32 v82, 0
	v_mov_b32_e32 v83, 0
	v_mov_b32_e32 v84, 0
	v_mov_b32_e32 v85, 0
	v_mov_b32_e32 v86, 0
	v_mov_b32_e32 v87, 0
	v_mov_b32_e32 v88, 0
	v_mov_b32_e32 v89, 0
	v_mov_b32_e32 v90, 0
	v_mov_b32_e32 v91, 0
	v_mov_b32_e32 v92, 0
	v_mov_b32_e32 v93, 0
	v_mov_b32_e32 v94, 0
	v_mov_b32_e32 v95, 0
	s_cbranch_vccnz .LBB0_174
	ds_read_b128 v[64:67], v242 offset:53248
	ds_read_b128 v[68:71], v242 offset:54272
	ds_read_b128 v[72:75], v242 offset:55296
	ds_read_b128 v[76:79], v242 offset:56320
	s_waitcnt lgkmcnt(3)
	v_mfma_f32_32x32x16_bf16 v[80:95], v[124:127], v[64:67], 0
	s_waitcnt lgkmcnt(2)
	v_mfma_f32_32x32x16_bf16 v[80:95], v[116:119], v[68:71], v[80:95]
	s_waitcnt lgkmcnt(1)
	v_mfma_f32_32x32x16_bf16 v[80:95], v[120:123], v[72:75], v[80:95]
	s_waitcnt lgkmcnt(0)
	v_mfma_f32_32x32x16_bf16 v[80:95], v[112:115], v[76:79], v[80:95]
.LBB0_174:
	v_mov_b32_e32 v64, 0
	s_sub_i32 s10, s5, 32
	s_cmp_le_i32 s10, s28
	s_cselect_b64 s[0:1], -1, 0
	s_and_b64 s[0:1], s[8:9], s[0:1]
	v_cndmask_b32_e64 v65, 0, 1, s[0:1]
	v_cmp_ne_u32_e64 s[40:41], 1, v65
	s_andn2_b64 vcc, exec, s[0:1]
	v_mov_b32_e32 v65, 0
	v_mov_b32_e32 v66, 0
	v_mov_b32_e32 v67, 0
	v_mov_b32_e32 v68, 0
	v_mov_b32_e32 v69, 0
	v_mov_b32_e32 v70, 0
	v_mov_b32_e32 v71, 0
	v_mov_b32_e32 v72, 0
	v_mov_b32_e32 v73, 0
	v_mov_b32_e32 v74, 0
	v_mov_b32_e32 v75, 0
	v_mov_b32_e32 v76, 0
	v_mov_b32_e32 v77, 0
	v_mov_b32_e32 v78, 0
	v_mov_b32_e32 v79, 0
	s_cbranch_vccnz .LBB0_176
	ds_read_b128 v[64:67], v242 offset:49152
	ds_read_b128 v[248:251], v242 offset:50176
	s_waitcnt lgkmcnt(1)
	v_mfma_f32_32x32x16_bf16 v[64:79], v[124:127], v[64:67], 0
	ds_read_b128 v[124:127], v242 offset:51200
	s_waitcnt lgkmcnt(1)
	v_mfma_f32_32x32x16_bf16 v[64:79], v[116:119], v[248:251], v[64:79]
	ds_read_b128 v[116:119], v242 offset:52224
	s_waitcnt lgkmcnt(1)
	v_mfma_f32_32x32x16_bf16 v[64:79], v[120:123], v[124:127], v[64:79]
	s_waitcnt lgkmcnt(0)
	v_mfma_f32_32x32x16_bf16 v[64:79], v[112:115], v[116:119], v[64:79]
